# hoisted fragment reads in all 12 GEMM loops, phase-13 expert table kept in registers, packed f32 scale multiplies of the phase-12 SwiGLU epilogue split into scalar f32 multiplies
# baseline (speedup 1.0000x reference)
;     __device__ __forceinline__ float qscale(const Unit& u) const { return ((u.pn >= 8 && u.pn <= 11) || u.pn == 17) ? 0.5f : 1.0f; }
;     ...
;         if constexpr (QM == 2) { const float qs0_ = g.qs * E.qscale(cur), qs1_ = qs0_ * g.qs_b1; _Pragma("unroll") for (int a = 0; a < 2; ++a) _Pragma("unroll") for (int b = 0; b < 2; ++b) _Pragma("unroll") for (int m = 0; m < 4; ++m) _Pragma("unroll") for (int n = 0; n < 2; ++n) { const v4i t_ = __builtin_bit_cast(v4i, acc[a][b][m][n]); acc[a][b][m][n] = (f32x4){(float)t_[0], (float)t_[1], (float)t_[2], (float)t_[3]} * (b == 0 ? qs0_ : qs1_); } }
;     __device__ __forceinline__ void operator()(EPI_ARGS) const {
;     ...
;                 for (int n = 0; n < 2; ++n) { f32x4 g = acc[ai][0][m][n], up = acc[ai][1][m][n];
;                     if constexpr (!PRE) { g = g * ascale; up = up * ascale; }
;                     if constexpr (FOLD) { g = (g - cg[n] * mu) * rs + dg[n]; up = (up - cu[n] * mu) * rs + du[n]; }
;                     if constexpr (!PRE) up = up * oscale;
; #pragma unroll
;                     for (int j = 0; j < 4; ++j) { const float e = __builtin_amdgcn_exp2f(g[j] * -1.4426950408889634f); r[n][j] = g[j] * __builtin_amdgcn_rcpf(1.0f + e) * up[j]; } }
.LBB0_4741:
	v_cvt_f32_i32_e32 v147, v121
	v_cvt_f32_i32_e32 v123, v123
	v_cvt_f32_i32_e32 v122, v122
	v_cvt_f32_i32_e32 v146, v120
	v_cvt_f32_i32_e32 v145, v125
	v_cvt_f32_i32_e32 v144, v124
	v_mul_f32_e32 v120, s28, v122
	v_mul_f32_e32 v121, s28, v123
	v_mul_f32_e32 v122, s28, v146
	v_mul_f32_e32 v123, s28, v147
	v_cvt_f32_i32_e32 v147, v113
	v_cvt_f32_i32_e32 v115, v115
	v_cvt_f32_i32_e32 v114, v114
	v_cvt_f32_i32_e32 v146, v112
	v_cvt_f32_i32_e32 v125, v127
	v_cvt_f32_i32_e32 v124, v126
	v_mul_f32_e32 v126, s28, v144
	v_mul_f32_e32 v127, s28, v145
	v_cvt_f32_i32_e32 v145, v117
	v_cvt_f32_i32_e32 v144, v116
	v_mul_f32_e32 v112, s28, v114
	v_mul_f32_e32 v113, s28, v115
	v_mul_f32_e32 v114, s28, v146
	v_mul_f32_e32 v115, s28, v147
	v_cvt_f32_i32_e32 v147, v105
	v_cvt_f32_i32_e32 v107, v107
	v_cvt_f32_i32_e32 v106, v106
	v_cvt_f32_i32_e32 v146, v104
	v_cvt_f32_i32_e32 v117, v119
	v_cvt_f32_i32_e32 v116, v118
	v_mul_f32_e32 v118, s28, v144
	v_mul_f32_e32 v119, s28, v145
	v_cvt_f32_i32_e32 v145, v109
	v_cvt_f32_i32_e32 v144, v108
	v_mul_f32_e32 v104, s28, v106
	v_mul_f32_e32 v105, s28, v107
	v_mul_f32_e32 v106, s28, v146
	v_mul_f32_e32 v107, s28, v147
	v_cvt_f32_i32_e32 v147, v97
	v_cvt_f32_i32_e32 v99, v99
	v_cvt_f32_i32_e32 v98, v98
	v_cvt_f32_i32_e32 v146, v96
	v_cvt_f32_i32_e32 v93, v93
	v_cvt_f32_i32_e32 v92, v92
	v_cvt_f32_i32_e32 v91, v91
	v_cvt_f32_i32_e32 v90, v90
	v_cvt_f32_i32_e32 v85, v85
	v_cvt_f32_i32_e32 v84, v84
	v_cvt_f32_i32_e32 v83, v83
	v_cvt_f32_i32_e32 v82, v82
	v_cvt_f32_i32_e32 v77, v77
	v_cvt_f32_i32_e32 v76, v76
	v_cvt_f32_i32_e32 v75, v75
	v_cvt_f32_i32_e32 v74, v74
	v_cvt_f32_i32_e32 v109, v111
	v_cvt_f32_i32_e32 v108, v110
	v_mul_f32_e32 v110, s28, v144
	v_mul_f32_e32 v111, s28, v145
	v_cvt_f32_i32_e32 v145, v101
	v_cvt_f32_i32_e32 v144, v100
	v_cvt_f32_i32_e32 v95, v95
	v_cvt_f32_i32_e32 v94, v94
	v_cvt_f32_i32_e32 v89, v89
	v_cvt_f32_i32_e32 v88, v88
	v_cvt_f32_i32_e32 v87, v87
	v_cvt_f32_i32_e32 v86, v86
	v_cvt_f32_i32_e32 v81, v81
	v_cvt_f32_i32_e32 v80, v80
	v_cvt_f32_i32_e32 v79, v79
	v_cvt_f32_i32_e32 v78, v78
	v_cvt_f32_i32_e32 v73, v73
	v_cvt_f32_i32_e32 v72, v72
	v_mul_f32_e32 v96, s28, v98
	v_mul_f32_e32 v97, s28, v99
	v_mul_f32_e32 v98, s28, v146
	v_mul_f32_e32 v99, s28, v147
	v_mul_f32_e32 v146, s30, v92
	v_mul_f32_e32 v147, s30, v93
	v_mul_f32_e32 v92, s30, v90
	v_mul_f32_e32 v93, s30, v91
	v_mul_f32_e32 v90, s30, v84
	v_mul_f32_e32 v91, s30, v85
	v_mul_f32_e32 v84, s30, v82
	v_mul_f32_e32 v85, s30, v83
	v_mul_f32_e32 v82, s30, v76
	v_mul_f32_e32 v83, s30, v77
	v_mul_f32_e32 v76, s30, v74
	v_mul_f32_e32 v77, s30, v75
	v_cvt_f32_i32_e32 v75, v65
	v_cvt_f32_i32_e32 v67, v67
	v_cvt_f32_i32_e32 v66, v66
	v_cvt_f32_i32_e32 v74, v64
	v_cvt_f32_i32_e32 v101, v103
	v_cvt_f32_i32_e32 v100, v102
	v_mul_f32_e32 v102, s28, v144
	v_mul_f32_e32 v103, s28, v145
	v_mul_f32_e32 v144, s30, v94
	v_mul_f32_e32 v145, s30, v95
	v_mul_f32_e32 v94, s30, v88
	v_mul_f32_e32 v95, s30, v89
	v_mul_f32_e32 v88, s30, v86
	v_mul_f32_e32 v89, s30, v87
	v_mul_f32_e32 v86, s30, v80
	v_mul_f32_e32 v87, s30, v81
	v_mul_f32_e32 v80, s30, v78
	v_mul_f32_e32 v81, s30, v79
	v_mul_f32_e32 v78, s30, v72
	v_mul_f32_e32 v79, s30, v73
	v_cvt_f32_i32_e32 v73, v69
	v_cvt_f32_i32_e32 v72, v68
	v_mul_f32_e32 v64, s30, v66
	v_mul_f32_e32 v65, s30, v67
	v_mul_f32_e32 v66, s30, v74
	v_mul_f32_e32 v67, s30, v75
	v_cvt_f32_i32_e32 v75, v57
	v_cvt_f32_i32_e32 v59, v59
	v_cvt_f32_i32_e32 v58, v58
	v_cvt_f32_i32_e32 v74, v56
	v_cvt_f32_i32_e32 v69, v71
	v_cvt_f32_i32_e32 v68, v70
	v_mul_f32_e32 v70, s30, v72
	v_mul_f32_e32 v71, s30, v73
	v_cvt_f32_i32_e32 v73, v61
	v_cvt_f32_i32_e32 v72, v60
	v_mul_f32_e32 v56, s28, v58
	v_mul_f32_e32 v57, s28, v59
	v_mul_f32_e32 v58, s28, v74
	v_mul_f32_e32 v59, s28, v75
	v_cvt_f32_i32_e32 v75, v49
	v_cvt_f32_i32_e32 v51, v51
	v_cvt_f32_i32_e32 v50, v50
	v_cvt_f32_i32_e32 v74, v48
	v_cvt_f32_i32_e32 v61, v63
	v_cvt_f32_i32_e32 v60, v62
	v_mul_f32_e32 v62, s28, v72
	v_mul_f32_e32 v63, s28, v73
	v_cvt_f32_i32_e32 v73, v53
	v_cvt_f32_i32_e32 v72, v52
	v_mul_f32_e32 v48, s28, v50
	v_mul_f32_e32 v49, s28, v51
	v_mul_f32_e32 v50, s28, v74
	v_mul_f32_e32 v51, s28, v75
	v_cvt_f32_i32_e32 v75, v41
	v_cvt_f32_i32_e32 v43, v43
	v_cvt_f32_i32_e32 v42, v42
	v_cvt_f32_i32_e32 v74, v40
	v_cvt_f32_i32_e32 v53, v55
	v_cvt_f32_i32_e32 v52, v54
	v_mul_f32_e32 v54, s28, v72
	v_mul_f32_e32 v55, s28, v73
	v_cvt_f32_i32_e32 v73, v45
	v_cvt_f32_i32_e32 v72, v44
	v_mul_f32_e32 v40, s28, v42
	v_mul_f32_e32 v41, s28, v43
	v_mul_f32_e32 v42, s28, v74
	v_mul_f32_e32 v43, s28, v75
	v_cvt_f32_i32_e32 v75, v33
	v_cvt_f32_i32_e32 v35, v35
	v_cvt_f32_i32_e32 v34, v34
	v_cvt_f32_i32_e32 v74, v32
	v_cvt_f32_i32_e32 v29, v29
	v_cvt_f32_i32_e32 v28, v28
	v_cvt_f32_i32_e32 v27, v27
	v_cvt_f32_i32_e32 v26, v26
	v_cvt_f32_i32_e32 v21, v21
	v_cvt_f32_i32_e32 v20, v20
	v_cvt_f32_i32_e32 v19, v19
	v_cvt_f32_i32_e32 v18, v18
	v_cvt_f32_i32_e32 v13, v13
	v_cvt_f32_i32_e32 v12, v12
	v_cvt_f32_i32_e32 v9, v9
	v_cvt_f32_i32_e32 v8, v8
	v_cvt_f32_i32_e32 v5, v5
	v_cvt_f32_i32_e32 v4, v4
	v_cvt_f32_i32_e32 v1, v1
	v_cvt_f32_i32_e32 v0, v0
	v_cvt_f32_i32_e32 v45, v47
	v_cvt_f32_i32_e32 v44, v46
	v_mul_f32_e32 v46, s28, v72
	v_mul_f32_e32 v47, s28, v73
	v_cvt_f32_i32_e32 v73, v37
	v_cvt_f32_i32_e32 v72, v36
	v_cvt_f32_i32_e32 v31, v31
	v_cvt_f32_i32_e32 v30, v30
	v_cvt_f32_i32_e32 v25, v25
	v_cvt_f32_i32_e32 v24, v24
	v_cvt_f32_i32_e32 v23, v23
	v_cvt_f32_i32_e32 v22, v22
	v_cvt_f32_i32_e32 v17, v17
	v_cvt_f32_i32_e32 v16, v16
	v_cvt_f32_i32_e32 v15, v15
	v_cvt_f32_i32_e32 v14, v14
	v_mul_f32_e32 v32, s28, v34
	v_mul_f32_e32 v33, s28, v35
	v_mul_f32_e32 v34, s28, v74
; __device__ __forceinline__ u32x4 pack8bf(const f32x4 a, const f32x4 b) { u32x4 w; w.x = cvt_pk_bf16(a[0], a[1]); w.y = cvt_pk_bf16(a[2], a[3]); w.z = cvt_pk_bf16(b[0], b[1]); w.w = cvt_pk_bf16(b[2], b[3]); return w; }
;     __device__ __forceinline__ void operator()(EPI_ARGS) const {
;     ...
;                 for (int n = 0; n < 2; ++n) { f32x4 g = acc[ai][0][m][n], up = acc[ai][1][m][n];
;                     if constexpr (!PRE) { g = g * ascale; up = up * ascale; }
;                     if constexpr (FOLD) { g = (g - cg[n] * mu) * rs + dg[n]; up = (up - cu[n] * mu) * rs + du[n]; }
;                     if constexpr (!PRE) up = up * oscale;
; #pragma unroll
;                     for (int j = 0; j < 4; ++j) { const float e = __builtin_amdgcn_exp2f(g[j] * -1.4426950408889634f); r[n][j] = g[j] * __builtin_amdgcn_rcpf(1.0f + e) * up[j]; } }
;                 if constexpr (F8OUT) *(u32x2*)((unsigned char*)O + (size_t)row * ldc + col0) = pack8fp8(r[0], r[1]);
;                 else *(u32x4*)((bf16_t*)O + (size_t)row * ldc + col0) = pack8bf(r[0], r[1]); }
	v_mul_f32_e32 v35, s28, v75
	v_mul_f32_e32 v74, s30, v28
	v_mul_f32_e32 v75, s30, v29
	v_mul_f32_e32 v28, s30, v26
	v_mul_f32_e32 v29, s30, v27
	v_mul_f32_e32 v26, s30, v20
	v_mul_f32_e32 v27, s30, v21
	v_mul_f32_e32 v20, s30, v18
	v_mul_f32_e32 v21, s30, v19
	v_mul_f32_e32 v18, s30, v12
	v_mul_f32_e32 v19, s30, v13
	v_mul_f32_e32 v12, s30, v8
	v_mul_f32_e32 v13, s30, v9
	v_mul_f32_e32 v8, s30, v4
	v_mul_f32_e32 v9, s30, v5
	v_mul_f32_e32 v4, s30, v0
	v_mul_f32_e32 v5, s30, v1
	v_mul_f32_e32 v0, 0xbfb8aa3b, v126
	v_exp_f32_e32 v1, v0
	v_mul_f32_e32 v0, 0xbfb8aa3b, v127
	v_cvt_f32_i32_e32 v37, v39
	v_cvt_f32_i32_e32 v36, v38
	v_mul_f32_e32 v38, s28, v72
	v_mul_f32_e32 v39, s28, v73
	v_mul_f32_e32 v72, s30, v30
	v_mul_f32_e32 v73, s30, v31
	v_mul_f32_e32 v30, s30, v24
	v_mul_f32_e32 v31, s30, v25
	v_mul_f32_e32 v24, s30, v22
	v_mul_f32_e32 v25, s30, v23
	v_mul_f32_e32 v22, s30, v16
	v_mul_f32_e32 v23, s30, v17
	v_mul_f32_e32 v16, s30, v14
	v_mul_f32_e32 v17, s30, v15
	v_exp_f32_e32 v14, v0
	v_add_f32_e32 v1, 1.0, v1
	v_rcp_f32_e32 v15, v1
	v_mul_f32_e32 v124, s28, v124
	v_mul_f32_e32 v125, s28, v125
	v_add_f32_e32 v1, 1.0, v14
	v_rcp_f32_e32 v14, v1
	v_mul_f32_e32 v15, v126, v15
	v_mul_f32_e32 v126, 0xbfb8aa3b, v124
	v_exp_f32_e32 v126, v126
	v_mul_f32_e32 v14, v127, v14
	v_mul_f32_e32 v127, 0xbfb8aa3b, v125
	v_exp_f32_e32 v127, v127
	v_mul_f32_e32 v15, v146, v15
	v_add_f32_e32 v126, 1.0, v126
	v_mul_f32_e32 v146, 0xbfb8aa3b, v122
	v_rcp_f32_e32 v126, v126
	v_add_f32_e32 v127, 1.0, v127
	v_exp_f32_e32 v146, v146
	v_rcp_f32_e32 v127, v127
	v_mul_f32_e32 v124, v124, v126
	v_mul_f32_e32 v14, v147, v14
	v_add_f32_e32 v126, 1.0, v146
	v_mul_f32_e32 v125, v125, v127
	v_rcp_f32_e32 v126, v126
	v_mul_f32_e32 v127, 0xbfb8aa3b, v123
	v_exp_f32_e32 v127, v127
	v_med3_f32 v15, v15, s63, v154
	v_mul_f32_e32 v122, v122, v126
	v_mul_f32_e32 v94, v94, v122
	v_add_f32_e32 v122, 1.0, v127
	v_mul_f32_e32 v126, 0xbfb8aa3b, v120
	v_rcp_f32_e32 v122, v122
	v_exp_f32_e32 v126, v126
	v_mul_f32_e32 v127, 0xbfb8aa3b, v121
	v_exp_f32_e32 v127, v127
	v_mul_f32_e32 v122, v123, v122
	v_add_f32_e32 v123, 1.0, v126
	v_rcp_f32_e32 v123, v123
	v_add_f32_e32 v126, 1.0, v127
	v_rcp_f32_e32 v126, v126
	v_med3_f32 v14, v14, s63, v154
	v_mul_f32_e32 v120, v120, v123
	v_mul_f32_e32 v120, v92, v120
	v_mul_f32_e32 v92, v121, v126
	v_mul_f32_e32 v121, v93, v92
	v_cvt_pk_fp8_f32 v92, v15, v14
	v_mul_f32_e32 v95, v95, v122
	v_mul_f32_e32 v124, v144, v124
	v_mul_f32_e32 v125, v145, v125
	v_med3_f32 v94, v94, s63, v154
	v_med3_f32 v95, v95, s63, v154
	v_med3_f32 v14, v124, s63, v154
	v_med3_f32 v15, v125, s63, v154
	v_cvt_pk_fp8_f32 v93, v94, v95
	v_cvt_pk_fp8_f32 v92, v14, v15 op_sel:[0,0,1]
	v_med3_f32 v14, v120, s63, v154
	v_mul_f32_e32 v120, 0xbfb8aa3b, v118
	v_med3_f32 v15, v121, s63, v154
	v_exp_f32_e32 v120, v120
	v_mul_f32_e32 v121, 0xbfb8aa3b, v119
	v_exp_f32_e32 v121, v121
	v_cvt_pk_fp8_f32 v93, v14, v15 op_sel:[0,0,1]
	v_lshl_add_u32 v156, s44, 8, v148
	v_lshl_or_b32 v0, s42, 7, v150
	v_mov_b64_e32 v[14:15], s[16:17]
	v_ashrrev_i32_e32 v1, 31, v0
	v_mad_i64_i32 v[94:95], s[4:5], v156, s64, v[14:15]
	v_add_f32_e32 v120, 1.0, v120
	v_mul_f32_e32 v116, s28, v116
	v_mul_f32_e32 v117, s28, v117
	v_lshl_add_u64 v[94:95], v[94:95], 0, v[0:1]
	v_rcp_f32_e32 v120, v120
	v_add_f32_e32 v121, 1.0, v121
	v_rcp_f32_e32 v121, v121
	global_store_dwordx2 v[94:95], v[92:93], off
	v_mul_f32_e32 v93, 0xbfb8aa3b, v116
	v_exp_f32_e32 v93, v93
	v_mul_f32_e32 v94, 0xbfb8aa3b, v117
	v_exp_f32_e32 v94, v94
	v_mul_f32_e32 v92, v118, v120
	v_mul_f32_e32 v90, v90, v92
	v_mul_f32_e32 v92, v119, v121
	v_mul_f32_e32 v91, v91, v92
	v_add_f32_e32 v92, 1.0, v93
	v_rcp_f32_e32 v92, v92
	v_add_f32_e32 v93, 1.0, v94
	v_mul_f32_e32 v94, 0xbfb8aa3b, v114
	v_rcp_f32_e32 v93, v93
	v_exp_f32_e32 v94, v94
	v_mul_f32_e32 v92, v116, v92
	v_mul_f32_e32 v88, v88, v92
	v_mul_f32_e32 v92, v117, v93
	v_add_f32_e32 v93, 1.0, v94
	v_rcp_f32_e32 v93, v93
	v_mul_f32_e32 v94, 0xbfb8aa3b, v115
	v_exp_f32_e32 v94, v94
	v_mul_f32_e32 v89, v89, v92
	v_mul_f32_e32 v92, v114, v93
	v_mul_f32_e32 v93, 0xbfb8aa3b, v112
	v_mul_f32_e32 v86, v86, v92
	v_add_f32_e32 v92, 1.0, v94
	v_exp_f32_e32 v93, v93
	v_mul_f32_e32 v94, 0xbfb8aa3b, v113
	v_exp_f32_e32 v94, v94
	v_rcp_f32_e32 v92, v92
	v_add_f32_e32 v93, 1.0, v93
	v_rcp_f32_e32 v93, v93
	v_add_f32_e32 v94, 1.0, v94
	v_rcp_f32_e32 v94, v94
	v_mul_f32_e32 v92, v115, v92
	v_mul_f32_e32 v87, v87, v92
	v_mul_f32_e32 v92, v112, v93
	v_mul_f32_e32 v92, v84, v92
	v_mul_f32_e32 v84, v113, v94
	v_mul_f32_e32 v93, v85, v84
	v_med3_f32 v85, v90, s63, v154
	v_med3_f32 v90, v91, s63, v154
	v_cvt_pk_fp8_f32 v84, v85, v90
	v_med3_f32 v86, v86, s63, v154
	v_med3_f32 v87, v87, s63, v154
	v_med3_f32 v88, v88, s63, v154
	v_med3_f32 v89, v89, s63, v154
	v_cvt_pk_fp8_f32 v85, v86, v87
	v_cvt_pk_fp8_f32 v84, v88, v89 op_sel:[0,0,1]
	v_mul_f32_e32 v88, 0xbfb8aa3b, v110
	v_exp_f32_e32 v88, v88
	v_mul_f32_e32 v89, 0xbfb8aa3b, v111
	v_med3_f32 v86, v92, s63, v154
	v_med3_f32 v87, v93, s63, v154
	v_exp_f32_e32 v89, v89
	v_cvt_pk_fp8_f32 v85, v86, v87 op_sel:[0,0,1]
	v_or_b32_e32 v94, 16, v156
	v_mad_i64_i32 v[86:87], s[4:5], v94, s64, v[14:15]
	v_add_f32_e32 v88, 1.0, v88
	v_mul_f32_e32 v108, s28, v108
	v_mul_f32_e32 v109, s28, v109
	v_lshl_add_u64 v[86:87], v[86:87], 0, v[0:1]
	v_rcp_f32_e32 v88, v88
	v_add_f32_e32 v89, 1.0, v89
	v_rcp_f32_e32 v89, v89
	global_store_dwordx2 v[86:87], v[84:85], off
	v_mul_f32_e32 v85, 0xbfb8aa3b, v108
	v_exp_f32_e32 v85, v85
	v_mul_f32_e32 v86, 0xbfb8aa3b, v109
	v_exp_f32_e32 v86, v86
	v_mul_f32_e32 v84, v110, v88
	v_mul_f32_e32 v82, v82, v84
	v_mul_f32_e32 v84, v111, v89
; __device__ __forceinline__ u32x4 pack8bf(const f32x4 a, const f32x4 b) { u32x4 w; w.x = cvt_pk_bf16(a[0], a[1]); w.y = cvt_pk_bf16(a[2], a[3]); w.z = cvt_pk_bf16(b[0], b[1]); w.w = cvt_pk_bf16(b[2], b[3]); return w; }
;     __device__ __forceinline__ void operator()(EPI_ARGS) const {
;     ...
;                 for (int n = 0; n < 2; ++n) { f32x4 g = acc[ai][0][m][n], up = acc[ai][1][m][n];
;                     if constexpr (!PRE) { g = g * ascale; up = up * ascale; }
;                     if constexpr (FOLD) { g = (g - cg[n] * mu) * rs + dg[n]; up = (up - cu[n] * mu) * rs + du[n]; }
;                     if constexpr (!PRE) up = up * oscale;
; #pragma unroll
;                     for (int j = 0; j < 4; ++j) { const float e = __builtin_amdgcn_exp2f(g[j] * -1.4426950408889634f); r[n][j] = g[j] * __builtin_amdgcn_rcpf(1.0f + e) * up[j]; } }
;                 if constexpr (F8OUT) *(u32x2*)((unsigned char*)O + (size_t)row * ldc + col0) = pack8fp8(r[0], r[1]);
;                 else *(u32x4*)((bf16_t*)O + (size_t)row * ldc + col0) = pack8bf(r[0], r[1]); }
	v_mul_f32_e32 v83, v83, v84
	v_add_f32_e32 v84, 1.0, v85
	v_rcp_f32_e32 v84, v84
	v_add_f32_e32 v85, 1.0, v86
	v_mul_f32_e32 v86, 0xbfb8aa3b, v106
	v_rcp_f32_e32 v85, v85
	v_exp_f32_e32 v86, v86
	v_mul_f32_e32 v84, v108, v84
	v_mul_f32_e32 v80, v80, v84
	v_mul_f32_e32 v84, v109, v85
	v_add_f32_e32 v85, 1.0, v86
	v_rcp_f32_e32 v85, v85
	v_mul_f32_e32 v86, 0xbfb8aa3b, v107
	v_exp_f32_e32 v86, v86
	v_mul_f32_e32 v81, v81, v84
	v_mul_f32_e32 v84, v106, v85
	v_mul_f32_e32 v85, 0xbfb8aa3b, v104
	v_mul_f32_e32 v78, v78, v84
	v_add_f32_e32 v84, 1.0, v86
	v_exp_f32_e32 v85, v85
	v_mul_f32_e32 v86, 0xbfb8aa3b, v105
	v_exp_f32_e32 v86, v86
	v_rcp_f32_e32 v84, v84
	v_add_f32_e32 v85, 1.0, v85
	v_rcp_f32_e32 v85, v85
	v_add_f32_e32 v86, 1.0, v86
	v_rcp_f32_e32 v86, v86
	v_mul_f32_e32 v84, v107, v84
	v_mul_f32_e32 v79, v79, v84
	v_mul_f32_e32 v84, v104, v85
	v_mul_f32_e32 v84, v76, v84
	v_mul_f32_e32 v76, v105, v86
	v_mul_f32_e32 v85, v77, v76
	v_med3_f32 v77, v82, s63, v154
	v_med3_f32 v82, v83, s63, v154
	v_cvt_pk_fp8_f32 v76, v77, v82
	v_med3_f32 v78, v78, s63, v154
	v_med3_f32 v79, v79, s63, v154
	v_med3_f32 v80, v80, s63, v154
	v_med3_f32 v81, v81, s63, v154
	v_cvt_pk_fp8_f32 v77, v78, v79
	v_cvt_pk_fp8_f32 v76, v80, v81 op_sel:[0,0,1]
	v_mul_f32_e32 v80, 0xbfb8aa3b, v102
	v_exp_f32_e32 v80, v80
	v_mul_f32_e32 v81, 0xbfb8aa3b, v103
	v_med3_f32 v78, v84, s63, v154
	v_med3_f32 v79, v85, s63, v154
	v_exp_f32_e32 v81, v81
	v_cvt_pk_fp8_f32 v77, v78, v79 op_sel:[0,0,1]
	v_or_b32_e32 v86, 32, v156
	v_mad_i64_i32 v[78:79], s[4:5], v86, s64, v[14:15]
	v_add_f32_e32 v80, 1.0, v80
	v_mul_f32_e32 v100, s28, v100
	v_mul_f32_e32 v101, s28, v101
	v_lshl_add_u64 v[78:79], v[78:79], 0, v[0:1]
	v_rcp_f32_e32 v80, v80
	v_add_f32_e32 v81, 1.0, v81
	v_rcp_f32_e32 v81, v81
	global_store_dwordx2 v[78:79], v[76:77], off
	v_mul_f32_e32 v77, 0xbfb8aa3b, v100
	v_exp_f32_e32 v77, v77
	v_mul_f32_e32 v78, 0xbfb8aa3b, v101
	v_exp_f32_e32 v78, v78
	v_mul_f32_e32 v76, v102, v80
	v_mul_f32_e32 v70, v70, v76
	v_mul_f32_e32 v76, v103, v81
	v_mul_f32_e32 v71, v71, v76
	v_add_f32_e32 v76, 1.0, v77
	v_rcp_f32_e32 v76, v76
	v_add_f32_e32 v77, 1.0, v78
	v_mul_f32_e32 v78, 0xbfb8aa3b, v98
	v_rcp_f32_e32 v77, v77
	v_exp_f32_e32 v78, v78
	v_mul_f32_e32 v68, s30, v68
	v_mul_f32_e32 v69, s30, v69
	v_mul_f32_e32 v76, v100, v76
	v_mul_f32_e32 v68, v68, v76
	v_mul_f32_e32 v76, v101, v77
	v_add_f32_e32 v77, 1.0, v78
	v_rcp_f32_e32 v77, v77
	v_mul_f32_e32 v78, 0xbfb8aa3b, v99
	v_exp_f32_e32 v78, v78
	v_mul_f32_e32 v69, v69, v76
	v_mul_f32_e32 v76, v98, v77
	v_mul_f32_e32 v77, 0xbfb8aa3b, v96
	v_mul_f32_e32 v66, v66, v76
	v_add_f32_e32 v76, 1.0, v78
	v_exp_f32_e32 v77, v77
	v_mul_f32_e32 v78, 0xbfb8aa3b, v97
	v_exp_f32_e32 v78, v78
	v_rcp_f32_e32 v76, v76
	v_add_f32_e32 v77, 1.0, v77
	v_rcp_f32_e32 v77, v77
	v_add_f32_e32 v78, 1.0, v78
	v_rcp_f32_e32 v78, v78
	v_mul_f32_e32 v76, v99, v76
	v_mul_f32_e32 v67, v67, v76
	v_mul_f32_e32 v76, v96, v77
	v_mul_f32_e32 v76, v64, v76
	v_mul_f32_e32 v64, v97, v78
	v_mul_f32_e32 v77, v65, v64
	v_med3_f32 v65, v70, s63, v154
	v_med3_f32 v70, v71, s63, v154
	v_cvt_pk_fp8_f32 v64, v65, v70
	v_med3_f32 v66, v66, s63, v154
	v_med3_f32 v67, v67, s63, v154
	v_cvt_pk_fp8_f32 v65, v66, v67
	v_med3_f32 v68, v68, s63, v154
	v_med3_f32 v69, v69, s63, v154
	v_cvt_pk_fp8_f32 v64, v68, v69 op_sel:[0,0,1]
	v_med3_f32 v66, v76, s63, v154
	v_med3_f32 v67, v77, s63, v154
	v_mul_f32_e32 v68, 0xbfb8aa3b, v62
	v_cvt_pk_fp8_f32 v65, v66, v67 op_sel:[0,0,1]
	v_exp_f32_e32 v68, v68
	v_mul_f32_e32 v69, 0xbfb8aa3b, v63
	v_or_b32_e32 v78, 48, v156
	v_exp_f32_e32 v69, v69
	v_mad_i64_i32 v[66:67], s[4:5], v78, s64, v[14:15]
	v_lshl_add_u64 v[66:67], v[66:67], 0, v[0:1]
	global_store_dwordx2 v[66:67], v[64:65], off
	v_add_f32_e32 v64, 1.0, v68
	v_rcp_f32_e32 v64, v64
	v_add_f32_e32 v65, 1.0, v69
	v_rcp_f32_e32 v65, v65
	v_mul_f32_e32 v60, s28, v60
	v_mul_f32_e32 v61, s28, v61
	v_mul_f32_e32 v62, v62, v64
	v_mul_f32_e32 v64, 0xbfb8aa3b, v60
	v_mul_f32_e32 v63, v63, v65
	v_exp_f32_e32 v64, v64
	v_mul_f32_e32 v65, 0xbfb8aa3b, v61
	v_exp_f32_e32 v65, v65
	v_mul_f32_e32 v67, 0xbfb8aa3b, v58
	v_add_f32_e32 v64, 1.0, v64
	v_rcp_f32_e32 v64, v64
	v_add_f32_e32 v65, 1.0, v65
	v_exp_f32_e32 v67, v67
	v_rcp_f32_e32 v65, v65
	v_mul_f32_e32 v60, v60, v64
	v_mul_f32_e32 v62, v74, v62
	v_add_f32_e32 v64, 1.0, v67
	v_mul_f32_e32 v61, v61, v65
	v_rcp_f32_e32 v64, v64
	v_mul_f32_e32 v65, 0xbfb8aa3b, v59
	v_exp_f32_e32 v65, v65
	v_mul_f32_e32 v63, v75, v63
	v_mul_f32_e32 v58, v58, v64
	v_mul_f32_e32 v30, v30, v58
	v_add_f32_e32 v58, 1.0, v65
	v_mul_f32_e32 v64, 0xbfb8aa3b, v56
	v_rcp_f32_e32 v58, v58
	v_exp_f32_e32 v64, v64
	v_mul_f32_e32 v65, 0xbfb8aa3b, v57
	v_exp_f32_e32 v65, v65
	v_mul_f32_e32 v58, v59, v58
	v_add_f32_e32 v59, 1.0, v64
	v_rcp_f32_e32 v59, v59
	v_add_f32_e32 v64, 1.0, v65
	v_rcp_f32_e32 v64, v64
	v_mul_f32_e32 v31, v31, v58
	v_mul_f32_e32 v56, v56, v59
	v_mul_f32_e32 v56, v28, v56
	v_mul_f32_e32 v28, v57, v64
	v_mul_f32_e32 v57, v29, v28
	v_med3_f32 v29, v62, s63, v154
	v_med3_f32 v58, v63, s63, v154
	v_cvt_pk_fp8_f32 v28, v29, v58
	v_med3_f32 v30, v30, s63, v154
	v_med3_f32 v31, v31, s63, v154
	v_cvt_pk_fp8_f32 v29, v30, v31
	v_med3_f32 v30, v56, s63, v154
	v_mul_f32_e32 v56, 0xbfb8aa3b, v54
	v_mul_f32_e32 v60, v72, v60
	v_mul_f32_e32 v61, v73, v61
	v_med3_f32 v31, v57, s63, v154
	v_exp_f32_e32 v56, v56
	v_mul_f32_e32 v57, 0xbfb8aa3b, v55
	v_med3_f32 v58, v60, s63, v154
	v_med3_f32 v59, v61, s63, v154
	v_exp_f32_e32 v57, v57
	v_cvt_pk_fp8_f32 v28, v58, v59 op_sel:[0,0,1]
	v_cvt_pk_fp8_f32 v29, v30, v31 op_sel:[0,0,1]
	v_add_u32_e32 v66, 0x80, v156
	v_mad_i64_i32 v[30:31], s[4:5], v66, s64, v[14:15]
; #define PG8_BAR __builtin_amdgcn_s_barrier()
; __device__ __forceinline__ u32x4 pack8bf(const f32x4 a, const f32x4 b) { u32x4 w; w.x = cvt_pk_bf16(a[0], a[1]); w.y = cvt_pk_bf16(a[2], a[3]); w.z = cvt_pk_bf16(b[0], b[1]); w.w = cvt_pk_bf16(b[2], b[3]); return w; }
;     ...
;         if (!has_next) break;
; #pragma unroll
;         for (int a = 0; a < 2; ++a)
; #pragma unroll
;             for (int b = 0; b < 2; ++b)
; #pragma unroll
;                 for (int m = 0; m < 4; ++m)
; #pragma unroll
;                     for (int n = 0; n < 2; ++n) acc[a][b][m][n] = (f32x4){0.f, 0.f, 0.f, 0.f};
;         cur = nxt; cA = nA; cB = nB; ++ui;
;         if (wr == 1) PG8_BAR;
;     __device__ __forceinline__ void operator()(EPI_ARGS) const {
;     ...
;                 for (int n = 0; n < 2; ++n) { f32x4 g = acc[ai][0][m][n], up = acc[ai][1][m][n];
;                     if constexpr (!PRE) { g = g * ascale; up = up * ascale; }
;                     if constexpr (FOLD) { g = (g - cg[n] * mu) * rs + dg[n]; up = (up - cu[n] * mu) * rs + du[n]; }
;                     if constexpr (!PRE) up = up * oscale;
; #pragma unroll
;                     for (int j = 0; j < 4; ++j) { const float e = __builtin_amdgcn_exp2f(g[j] * -1.4426950408889634f); r[n][j] = g[j] * __builtin_amdgcn_rcpf(1.0f + e) * up[j]; } }
;                 if constexpr (F8OUT) *(u32x2*)((unsigned char*)O + (size_t)row * ldc + col0) = pack8fp8(r[0], r[1]);
;                 else *(u32x4*)((bf16_t*)O + (size_t)row * ldc + col0) = pack8bf(r[0], r[1]); }
	v_add_f32_e32 v56, 1.0, v56
	v_mul_f32_e32 v52, s28, v52
	v_mul_f32_e32 v53, s28, v53
	v_lshl_add_u64 v[30:31], v[30:31], 0, v[0:1]
	v_rcp_f32_e32 v56, v56
	v_add_f32_e32 v57, 1.0, v57
	v_rcp_f32_e32 v57, v57
	global_store_dwordx2 v[30:31], v[28:29], off
	v_mul_f32_e32 v29, 0xbfb8aa3b, v52
	v_exp_f32_e32 v29, v29
	v_mul_f32_e32 v30, 0xbfb8aa3b, v53
	v_exp_f32_e32 v30, v30
	v_mul_f32_e32 v28, v54, v56
	v_mul_f32_e32 v26, v26, v28
	v_mul_f32_e32 v28, v55, v57
	v_mul_f32_e32 v27, v27, v28
	v_add_f32_e32 v28, 1.0, v29
	v_rcp_f32_e32 v28, v28
	v_add_f32_e32 v29, 1.0, v30
	v_mul_f32_e32 v30, 0xbfb8aa3b, v50
	v_rcp_f32_e32 v29, v29
	v_exp_f32_e32 v30, v30
	v_mul_f32_e32 v28, v52, v28
	v_mul_f32_e32 v24, v24, v28
	v_mul_f32_e32 v28, v53, v29
	v_add_f32_e32 v29, 1.0, v30
	v_rcp_f32_e32 v29, v29
	v_mul_f32_e32 v30, 0xbfb8aa3b, v51
	v_exp_f32_e32 v30, v30
	v_mul_f32_e32 v25, v25, v28
	v_mul_f32_e32 v28, v50, v29
	v_mul_f32_e32 v29, 0xbfb8aa3b, v48
	v_mul_f32_e32 v22, v22, v28
	v_add_f32_e32 v28, 1.0, v30
	v_exp_f32_e32 v29, v29
	v_mul_f32_e32 v30, 0xbfb8aa3b, v49
	v_exp_f32_e32 v30, v30
	v_rcp_f32_e32 v28, v28
	v_add_f32_e32 v29, 1.0, v29
	v_rcp_f32_e32 v29, v29
	v_add_f32_e32 v30, 1.0, v30
	v_rcp_f32_e32 v30, v30
	v_mul_f32_e32 v28, v51, v28
	v_mul_f32_e32 v23, v23, v28
	v_mul_f32_e32 v28, v48, v29
	v_mul_f32_e32 v28, v20, v28
	v_mul_f32_e32 v20, v49, v30
	v_mul_f32_e32 v29, v21, v20
	v_med3_f32 v21, v26, s63, v154
	v_med3_f32 v26, v27, s63, v154
	v_cvt_pk_fp8_f32 v20, v21, v26
	v_med3_f32 v22, v22, s63, v154
	v_med3_f32 v23, v23, s63, v154
	v_med3_f32 v24, v24, s63, v154
	v_med3_f32 v25, v25, s63, v154
	v_cvt_pk_fp8_f32 v21, v22, v23
	v_cvt_pk_fp8_f32 v20, v24, v25 op_sel:[0,0,1]
	v_mul_f32_e32 v24, 0xbfb8aa3b, v46
	v_exp_f32_e32 v24, v24
	v_mul_f32_e32 v25, 0xbfb8aa3b, v47
	v_med3_f32 v22, v28, s63, v154
	v_med3_f32 v23, v29, s63, v154
	v_exp_f32_e32 v25, v25
	v_cvt_pk_fp8_f32 v21, v22, v23 op_sel:[0,0,1]
	v_add_u32_e32 v30, 0x90, v156
	v_mad_i64_i32 v[22:23], s[4:5], v30, s64, v[14:15]
	v_add_f32_e32 v24, 1.0, v24
	v_mul_f32_e32 v44, s28, v44
	v_mul_f32_e32 v45, s28, v45
	v_lshl_add_u64 v[22:23], v[22:23], 0, v[0:1]
	v_rcp_f32_e32 v24, v24
	v_add_f32_e32 v25, 1.0, v25
	v_rcp_f32_e32 v25, v25
	global_store_dwordx2 v[22:23], v[20:21], off
	v_mul_f32_e32 v21, 0xbfb8aa3b, v44
	v_exp_f32_e32 v21, v21
	v_mul_f32_e32 v22, 0xbfb8aa3b, v45
	v_exp_f32_e32 v22, v22
	v_mul_f32_e32 v20, v46, v24
	v_mul_f32_e32 v18, v18, v20
	v_mul_f32_e32 v20, v47, v25
	v_mul_f32_e32 v19, v19, v20
	v_add_f32_e32 v20, 1.0, v21
	v_rcp_f32_e32 v20, v20
	v_add_f32_e32 v21, 1.0, v22
	v_mul_f32_e32 v22, 0xbfb8aa3b, v42
	v_rcp_f32_e32 v21, v21
	v_exp_f32_e32 v22, v22
	v_mul_f32_e32 v20, v44, v20
	v_mul_f32_e32 v16, v16, v20
	v_mul_f32_e32 v20, v45, v21
	v_add_f32_e32 v21, 1.0, v22
	v_rcp_f32_e32 v21, v21
	v_mul_f32_e32 v22, 0xbfb8aa3b, v43
	v_exp_f32_e32 v22, v22
	v_mul_f32_e32 v17, v17, v20
	v_mul_f32_e32 v20, v42, v21
	v_mul_f32_e32 v21, 0xbfb8aa3b, v40
	v_mul_f32_e32 v12, v12, v20
	v_add_f32_e32 v20, 1.0, v22
	v_exp_f32_e32 v21, v21
	v_mul_f32_e32 v22, 0xbfb8aa3b, v41
	v_exp_f32_e32 v22, v22
	v_rcp_f32_e32 v20, v20
	v_add_f32_e32 v21, 1.0, v21
	v_cvt_f32_i32_e32 v11, v11
	v_cvt_f32_i32_e32 v10, v10
	v_rcp_f32_e32 v21, v21
	v_add_f32_e32 v22, 1.0, v22
	v_rcp_f32_e32 v22, v22
	v_mul_f32_e32 v20, v43, v20
	v_mul_f32_e32 v10, s30, v10
	v_mul_f32_e32 v11, s30, v11
	v_mul_f32_e32 v13, v13, v20
	v_mul_f32_e32 v20, v40, v21
	v_mul_f32_e32 v20, v10, v20
	v_mul_f32_e32 v10, v41, v22
	v_mul_f32_e32 v21, v11, v10
	v_med3_f32 v11, v18, s63, v154
	v_med3_f32 v18, v19, s63, v154
	v_cvt_pk_fp8_f32 v10, v11, v18
	v_med3_f32 v12, v12, s63, v154
	v_med3_f32 v13, v13, s63, v154
	v_med3_f32 v16, v16, s63, v154
	v_med3_f32 v17, v17, s63, v154
	v_cvt_pk_fp8_f32 v11, v12, v13
	v_cvt_pk_fp8_f32 v10, v16, v17 op_sel:[0,0,1]
	v_mul_f32_e32 v16, 0xbfb8aa3b, v38
	v_exp_f32_e32 v16, v16
	v_mul_f32_e32 v17, 0xbfb8aa3b, v39
	v_med3_f32 v12, v20, s63, v154
	v_med3_f32 v13, v21, s63, v154
	v_exp_f32_e32 v17, v17
	v_cvt_pk_fp8_f32 v11, v12, v13 op_sel:[0,0,1]
	v_add_u32_e32 v22, 0xa0, v156
	v_mad_i64_i32 v[12:13], s[4:5], v22, s64, v[14:15]
	v_add_f32_e32 v16, 1.0, v16
	v_mul_f32_e32 v36, s28, v36
	v_mul_f32_e32 v37, s28, v37
	v_lshl_add_u64 v[12:13], v[12:13], 0, v[0:1]
	v_rcp_f32_e32 v16, v16
	v_add_f32_e32 v17, 1.0, v17
	v_rcp_f32_e32 v17, v17
	global_store_dwordx2 v[12:13], v[10:11], off
	v_mul_f32_e32 v11, 0xbfb8aa3b, v36
	v_exp_f32_e32 v11, v11
	v_mul_f32_e32 v12, 0xbfb8aa3b, v37
	v_exp_f32_e32 v12, v12
	v_mul_f32_e32 v10, v38, v16
	v_mul_f32_e32 v8, v8, v10
	v_mul_f32_e32 v10, v39, v17
	v_mul_f32_e32 v9, v9, v10
	v_add_f32_e32 v10, 1.0, v11
	v_cvt_f32_i32_e32 v7, v7
	v_cvt_f32_i32_e32 v6, v6
	v_rcp_f32_e32 v10, v10
	v_add_f32_e32 v11, 1.0, v12
	v_mul_f32_e32 v12, 0xbfb8aa3b, v34
	v_rcp_f32_e32 v11, v11
	v_exp_f32_e32 v12, v12
	v_mul_f32_e32 v6, s30, v6
	v_mul_f32_e32 v7, s30, v7
	v_mul_f32_e32 v10, v36, v10
	v_mul_f32_e32 v6, v6, v10
	v_mul_f32_e32 v10, v37, v11
	v_add_f32_e32 v11, 1.0, v12
	v_rcp_f32_e32 v11, v11
	v_mul_f32_e32 v12, 0xbfb8aa3b, v35
	v_exp_f32_e32 v12, v12
	v_mul_f32_e32 v7, v7, v10
	v_mul_f32_e32 v10, v34, v11
	v_mul_f32_e32 v11, 0xbfb8aa3b, v32
	v_mul_f32_e32 v4, v4, v10
	v_add_f32_e32 v10, 1.0, v12
	v_exp_f32_e32 v11, v11
	v_mul_f32_e32 v12, 0xbfb8aa3b, v33
	v_exp_f32_e32 v12, v12
	v_rcp_f32_e32 v10, v10
	v_add_f32_e32 v11, 1.0, v11
	v_cvt_f32_i32_e32 v3, v3
	v_cvt_f32_i32_e32 v2, v2
	v_rcp_f32_e32 v11, v11
	v_add_f32_e32 v12, 1.0, v12
	v_rcp_f32_e32 v12, v12
	v_mul_f32_e32 v10, v35, v10
	v_mul_f32_e32 v2, s30, v2
	v_mul_f32_e32 v3, s30, v3
	v_mul_f32_e32 v5, v5, v10
	v_mul_f32_e32 v10, v32, v11
	v_mul_f32_e32 v10, v2, v10
	v_mul_f32_e32 v2, v33, v12
	v_mul_f32_e32 v11, v3, v2
	v_med3_f32 v3, v8, s63, v154
	v_med3_f32 v8, v9, s63, v154
	v_cvt_pk_fp8_f32 v2, v3, v8
	v_med3_f32 v4, v4, s63, v154
	v_med3_f32 v5, v5, s63, v154
	v_cvt_pk_fp8_f32 v3, v4, v5
	v_med3_f32 v6, v6, s63, v154
	v_med3_f32 v7, v7, s63, v154
	v_med3_f32 v4, v10, s63, v154
	v_med3_f32 v5, v11, s63, v154
	v_cvt_pk_fp8_f32 v2, v6, v7 op_sel:[0,0,1]
	v_cvt_pk_fp8_f32 v3, v4, v5 op_sel:[0,0,1]
	v_add_u32_e32 v12, 0xb0, v156
	v_mad_i64_i32 v[4:5], s[4:5], v12, s64, v[14:15]
	v_lshl_add_u64 v[0:1], v[4:5], 0, v[0:1]
	s_and_b64 vcc, exec, s[2:3]
	s_mov_b64 s[2:3], -1
	global_store_dwordx2 v[0:1], v[2:3], off
	s_cbranch_vccnz .LBB0_4732
	s_andn2_b64 vcc, exec, s[14:15]
	s_cbranch_vccnz .LBB0_4731
	s_barrier
	s_branch .LBB0_4731
